# v46: buffer_inv dropped at the barriers whose next phase only reads lines wholly written by one owner and never touched by the reader since its last invalidate (GLU->ATT, WO->LN1, LN1->UP, UP->fixup,
# speedup vs baseline: 1.0163x; 1.0163x over previous
; __device__ __forceinline__ unsigned xb_ld(unsigned* p)              { return __hip_atomic_load(p, __ATOMIC_RELAXED, __HIP_MEMORY_SCOPE_AGENT); }
; __device__ __forceinline__ unsigned xb_add(unsigned* p, unsigned v) { return __hip_atomic_fetch_add(p, v, __ATOMIC_RELAXED, __HIP_MEMORY_SCOPE_AGENT); }
; #define XB_SPIN(cond, bar) do { unsigned _sp = 0; while (cond) { __builtin_amdgcn_s_sleep(1); \
;     if ((++_sp & 255u) == 0u) { if (xb_ld(&(bar)[XB_TMO])) break; if (_sp > XB_SPIN_CAP) { atomicAdd(&(bar)[XB_TMO], 1u); break; } } } } while (0)
;     __device__ __forceinline__ bool next(int i, int& pm, int& pn, int& k0, int& nk, int& slice, int& src) const {
;         const long L = (long)i * G + c;
;         pm = 0; pn = 0; k0 = 0; nk = nt; slice = -1; src = 0;
;         if (L < nwg) {
;             int wgid = (int)L; { const int q = nwg / NXCD, r = nwg % NXCD, xcd = wgid % NXCD, off = wgid / NXCD; wgid = (xcd < r ? xcd * (q + 1) : r * (q + 1) + (xcd - r) * q) + off; }
;             const int nig = WGM * nN, gid = wgid / nig, fm = gid * WGM, gsz = (nM - fm) < WGM ? (nM - fm) : WGM;
;             pm = fm + ((wgid % nig) % gsz); pn = (wgid % nig) / gsz; return true;
; __device__ __forceinline__ void xcd_barrier(const XcdBarrier& b) {
;     ...
;             else XB_SPIN(xb_ld(&bar[XB_TOPGEN]) == tg, bar);
;             __builtin_amdgcn_fence(__ATOMIC_ACQUIRE, "agent");
;             xb_add(&bar[XB_XGEN(b.x)], 1u);
;             asm volatile("s_waitcnt vmcnt(0)" ::: "memory");
;         } else {
;             XB_SPIN(xb_ld(&bar[XB_XGEN(b.x)]) == gen, bar);
;             __builtin_amdgcn_fence(__ATOMIC_ACQUIRE, "agent");
;             asm volatile("s_waitcnt vmcnt(0)" ::: "memory");
;         }
;     }
;     __syncthreads();
.Lfb3_spin:
	global_load_dword v5, v4, s[4:5] sc1
	s_waitcnt vmcnt(0)
	v_cmp_ge_u32_e32 vcc, v5, v3
	s_cbranch_vccnz .Lfb3_done
	s_sleep 1
	s_add_u32 s6, s6, 1
	s_cmp_lt_u32 s6, 0x200000
	s_cbranch_scc1 .Lfb3_spin
.Lfb3_done:
	s_waitcnt vmcnt(0)
.LBB0_720:
	s_or_b64 exec, exec, s[0:1]
	v_readlane_b32 s0, v244, 60
	v_mov_b32_e32 v10, v0
	v_readlane_b32 s1, v244, 61
	s_waitcnt lgkmcnt(0)
	s_barrier
	s_andn2_b64 vcc, exec, s[0:1]
	v_readfirstlane_b32 s8, v10
	s_cbranch_vccnz .LBB0_744
	v_readlane_b32 s0, v244, 59
	s_lshr_b32 s0, s0, 29
	v_readlane_b32 s1, v244, 33
	s_add_i32 s5, s1, s0
	s_and_b32 s0, s5, -8
	s_sub_i32 s6, s1, s0
	s_cmp_gt_i32 s6, -1
	s_cbranch_scc0 .LBB0_723
	s_lshl_b32 s4, s6, 5
	s_cbranch_execz .LBB0_724
	s_branch .LBB0_725

; __device__ __forceinline__ unsigned xb_ld(unsigned* p)              { return __hip_atomic_load(p, __ATOMIC_RELAXED, __HIP_MEMORY_SCOPE_AGENT); }
; __device__ __forceinline__ unsigned xb_add(unsigned* p, unsigned v) { return __hip_atomic_fetch_add(p, v, __ATOMIC_RELAXED, __HIP_MEMORY_SCOPE_AGENT); }
; #define XB_SPIN(cond, bar) do { unsigned _sp = 0; while (cond) { __builtin_amdgcn_s_sleep(1); \
;     if ((++_sp & 255u) == 0u) { if (xb_ld(&(bar)[XB_TMO])) break; if (_sp > XB_SPIN_CAP) { atomicAdd(&(bar)[XB_TMO], 1u); break; } } } } while (0)
; template <int WHICH>
; __device__ __forceinline__ void ln_phase(const Params& p) {
;   const int lane = threadIdx.x & 63, wid = threadIdx.x >> 6;
;   const int gw = blockIdx.x * NWAVE + wid, NGW = gridDim.x * NWAVE;
;   const float* gam = p.in[WHICH == 1 ? 20 : 26]; const float* bet = p.in[WHICH == 1 ? 21 : 27];
;   f32x4 gv[4], bv[4];
; #pragma unroll
;   for (int j = 0; j < 4; ++j) { gv[j] = *(const f32x4*)(gam + j * 256 + lane * 4); bv[j] = *(const f32x4*)(bet + j * 256 + lane * 4); }
;   for (int rp = gw; rp < MP / 2; rp += NGW) ln_rows<WHICH, 2>(p, rp * 2, lane, gv, bv);
; __device__ __forceinline__ void xcd_barrier(const XcdBarrier& b) {
;     ...
;             else XB_SPIN(xb_ld(&bar[XB_TOPGEN]) == tg, bar);
;             __builtin_amdgcn_fence(__ATOMIC_ACQUIRE, "agent");
;             xb_add(&bar[XB_XGEN(b.x)], 1u);
;             asm volatile("s_waitcnt vmcnt(0)" ::: "memory");
;         } else {
;             XB_SPIN(xb_ld(&bar[XB_XGEN(b.x)]) == gen, bar);
;             __builtin_amdgcn_fence(__ATOMIC_ACQUIRE, "agent");
;             asm volatile("s_waitcnt vmcnt(0)" ::: "memory");
;         }
;     }
;     __syncthreads();
.Lfb5_spin:
	global_load_dword v5, v4, s[4:5] sc1
	s_waitcnt vmcnt(0)
	v_cmp_ge_u32_e32 vcc, v5, v3
	s_cbranch_vccnz .Lfb5_done
	s_sleep 1
	s_add_u32 s6, s6, 1
	s_cmp_lt_u32 s6, 0x200000
	s_cbranch_scc1 .Lfb5_spin
.Lfb5_done:
	s_waitcnt vmcnt(0)
.LBB0_889:
	s_or_b64 exec, exec, s[0:1]
	v_readlane_b32 s4, v244, 35
	v_and_b32_e32 v34, 0xfc, v1
	v_readlane_b32 s8, v244, 39
	v_readlane_b32 s9, v244, 40
	v_readlane_b32 s10, v244, 41
	v_readlane_b32 s11, v244, 42
	v_readlane_b32 s12, v244, 43
	v_readlane_b32 s13, v244, 44
	v_lshlrev_b32_e32 v188, 2, v34
	v_readlane_b32 s14, v244, 45
	v_readlane_b32 s15, v244, 46
	s_mov_b64 s[8:9], s[12:13]
	s_waitcnt lgkmcnt(0)
	s_barrier
	s_mov_b64 s[10:11], s[14:15]
	global_load_dwordx4 v[2:5], v188, s[8:9]
	global_load_dwordx4 v[6:9], v188, s[10:11]
	global_load_dwordx4 v[10:13], v188, s[8:9] offset:1024
	global_load_dwordx4 v[14:17], v188, s[10:11] offset:1024
	global_load_dwordx4 v[18:21], v188, s[8:9] offset:2048
	global_load_dwordx4 v[22:25], v188, s[10:11] offset:2048
	global_load_dwordx4 v[26:29], v188, s[8:9] offset:3072
	global_load_dwordx4 v[30:33], v188, s[10:11] offset:3072
	v_readlane_b32 s5, v244, 36
	s_movk_i32 s0, 0x2000
	v_mov_b32_e32 v191, 0
	v_cmp_gt_i32_e64 s[4:5], s0, v182
	v_lshlrev_b32_e32 v190, 1, v34
	v_lshl_add_u32 v192, v183, 1, s3
	v_readlane_b32 s6, v244, 37
	v_readlane_b32 s7, v244, 38
	v_readlane_b32 s16, v244, 47
	v_readlane_b32 s17, v244, 48
	v_readlane_b32 s18, v244, 49
	v_readlane_b32 s19, v244, 50
	s_and_saveexec_b64 s[0:1], s[4:5]
	s_cbranch_execz .LBB0_892
	v_mbcnt_hi_u32_b32 v34, -1, v185
	v_and_b32_e32 v35, 64, v34
	v_add_u32_e32 v35, 64, v35
	v_xor_b32_e32 v36, 1, v34
	v_cmp_lt_i32_e32 vcc, v36, v35
	v_lshl_add_u32 v38, v183, 1, s3
	s_lshl_b32 s3, s33, 4
	v_cndmask_b32_e32 v36, v34, v36, vcc
	v_lshlrev_b32_e32 v41, 2, v36
	v_xor_b32_e32 v36, 2, v34
	v_cmp_lt_i32_e32 vcc, v36, v35
	s_mov_b64 s[6:7], 0
	s_mov_b32 s8, 0x3a800000
	v_cndmask_b32_e32 v36, v34, v36, vcc
	v_lshlrev_b32_e32 v78, 2, v36
	v_xor_b32_e32 v36, 4, v34
	v_cmp_lt_i32_e32 vcc, v36, v35
	s_mov_b32 s9, 0x800000
	s_movk_i32 s10, 0x1fff
	v_cndmask_b32_e32 v36, v34, v36, vcc
	v_lshlrev_b32_e32 v79, 2, v36
	v_xor_b32_e32 v36, 8, v34
	v_cmp_lt_i32_e32 vcc, v36, v35
	v_mov_b32_e32 v40, 0x3727c5ac
	v_mov_b32_e32 v83, v182
	v_cndmask_b32_e32 v36, v34, v36, vcc
	v_lshlrev_b32_e32 v80, 2, v36
	v_xor_b32_e32 v36, 16, v34
	v_cmp_lt_i32_e32 vcc, v36, v35
	s_nop 1
	v_cndmask_b32_e32 v36, v34, v36, vcc
	v_lshlrev_b32_e32 v81, 2, v36
	v_xor_b32_e32 v36, 32, v34
	v_cmp_lt_i32_e32 vcc, v36, v35
	s_nop 1
	v_cndmask_b32_e32 v34, v34, v36, vcc
	v_lshlrev_b32_e32 v82, 2, v34
	v_lshl_add_u64 v[34:35], s[96:97], 0, v[190:191]
	v_lshl_add_u64 v[36:37], s[20:21], 0, v[190:191]

; __device__ __forceinline__ unsigned xb_ld(unsigned* p)              { return __hip_atomic_load(p, __ATOMIC_RELAXED, __HIP_MEMORY_SCOPE_AGENT); }
; __device__ __forceinline__ unsigned xb_add(unsigned* p, unsigned v) { return __hip_atomic_fetch_add(p, v, __ATOMIC_RELAXED, __HIP_MEMORY_SCOPE_AGENT); }
; #define XB_SPIN(cond, bar) do { unsigned _sp = 0; while (cond) { __builtin_amdgcn_s_sleep(1); \
;     if ((++_sp & 255u) == 0u) { if (xb_ld(&(bar)[XB_TMO])) break; if (_sp > XB_SPIN_CAP) { atomicAdd(&(bar)[XB_TMO], 1u); break; } } } } while (0)
;     __device__ __forceinline__ bool next(int i, int& pm, int& pn, int& k0, int& nk, int& slice, int& src) const {
;         const long L = (long)i * G + c;
;         pm = 0; pn = 0; k0 = 0; nk = nt; slice = -1; src = 0;
;         if (L < nwg) {
;             int wgid = (int)L; { const int q = nwg / NXCD, r = nwg % NXCD, xcd = wgid % NXCD, off = wgid / NXCD; wgid = (xcd < r ? xcd * (q + 1) : r * (q + 1) + (xcd - r) * q) + off; }
;             const int nig = WGM * nN, gid = wgid / nig, fm = gid * WGM, gsz = (nM - fm) < WGM ? (nM - fm) : WGM;
;             pm = fm + ((wgid % nig) % gsz); pn = (wgid % nig) / gsz; return true;
; __device__ __forceinline__ void xcd_barrier(const XcdBarrier& b) {
;     ...
;             else XB_SPIN(xb_ld(&bar[XB_TOPGEN]) == tg, bar);
;             __builtin_amdgcn_fence(__ATOMIC_ACQUIRE, "agent");
;             xb_add(&bar[XB_XGEN(b.x)], 1u);
;             asm volatile("s_waitcnt vmcnt(0)" ::: "memory");
;         } else {
;             XB_SPIN(xb_ld(&bar[XB_XGEN(b.x)]) == gen, bar);
;             __builtin_amdgcn_fence(__ATOMIC_ACQUIRE, "agent");
;             asm volatile("s_waitcnt vmcnt(0)" ::: "memory");
;         }
;     }
;     __syncthreads();
.Lfb6_spin:
	global_load_dword v5, v4, s[8:9] sc1
	s_waitcnt vmcnt(0)
	v_cmp_ge_u32_e32 vcc, v5, v3
	s_cbranch_vccnz .Lfb6_done
	s_sleep 1
	s_add_u32 s3, s3, 1
	s_cmp_lt_u32 s3, 0x200000
	s_cbranch_scc1 .Lfb6_spin
.Lfb6_done:
	s_waitcnt vmcnt(0)
.LBB0_951:
	s_or_b64 exec, exec, s[6:7]
	v_readlane_b32 s3, v244, 33
	s_waitcnt vmcnt(5)
	v_mov_b32_e32 v10, v0
	s_cmpk_lt_i32 s3, 0x5ac
	s_waitcnt lgkmcnt(0)
	s_barrier
	s_mov_b32 s54, 0
	v_readfirstlane_b32 s10, v10
	s_cselect_b64 s[6:7], -1, 0
	s_cmpk_gt_i32 s3, 0x5ab
	s_mov_b32 s18, 0
	s_cbranch_scc1 .LBB0_957
	v_readlane_b32 s0, v244, 59
	s_lshr_b32 s3, s0, 29
	v_readlane_b32 s9, v244, 33
	s_nop 3
	s_sub_u32 s98, s9, 172
	s_cmp_lt_u32 s98, 44
	s_cbranch_scc0 .Lperm7a_done
	s_lshl_b32 s98, s98, 3
	s_add_u32 s9, s98, 1103

; __device__ __forceinline__ unsigned xb_ld(unsigned* p)              { return __hip_atomic_load(p, __ATOMIC_RELAXED, __HIP_MEMORY_SCOPE_AGENT); }
; __device__ __forceinline__ unsigned xb_add(unsigned* p, unsigned v) { return __hip_atomic_fetch_add(p, v, __ATOMIC_RELAXED, __HIP_MEMORY_SCOPE_AGENT); }
; #define XB_SPIN(cond, bar) do { unsigned _sp = 0; while (cond) { __builtin_amdgcn_s_sleep(1); \
;     if ((++_sp & 255u) == 0u) { if (xb_ld(&(bar)[XB_TMO])) break; if (_sp > XB_SPIN_CAP) { atomicAdd(&(bar)[XB_TMO], 1u); break; } } } } while (0)
; __device__ __forceinline__ void fixup_phase(const Params& p) {
;   unsigned char* ws = p.ws;
;   const int gt = blockIdx.x * NTHR + threadIdx.x, NGT = gridDim.x * NTHR;
;   const float* HA0 = (const float*)(ws + OFF_HA0); const float* HG0 = (const float*)(ws + OFF_HG0); const float* HA1 = (const float*)(ws + OFF_HA1);
;   bf16_t* H = (bf16_t*)(ws + OFF_H);
;   constexpr int NJ4 = DFF / 4;
;   for (int i = gt; i < NRB * 2 * NJ4; i += NGT) {
;     const int j4 = i % NJ4, rl = (i / NJ4) & 1, rb = i / (2 * NJ4);
; __device__ __forceinline__ void xcd_barrier(const XcdBarrier& b) {
;     ...
;             else XB_SPIN(xb_ld(&bar[XB_TOPGEN]) == tg, bar);
;             __builtin_amdgcn_fence(__ATOMIC_ACQUIRE, "agent");
;             xb_add(&bar[XB_XGEN(b.x)], 1u);
;             asm volatile("s_waitcnt vmcnt(0)" ::: "memory");
;         } else {
;             XB_SPIN(xb_ld(&bar[XB_XGEN(b.x)]) == gen, bar);
;             __builtin_amdgcn_fence(__ATOMIC_ACQUIRE, "agent");
;             asm volatile("s_waitcnt vmcnt(0)" ::: "memory");
;         }
;     }
;     __syncthreads();
.Lfb7_spin:
	global_load_dword v5, v4, s[8:9] sc1
	s_waitcnt vmcnt(0)
	v_cmp_ge_u32_e32 vcc, v5, v3
	s_cbranch_vccnz .Lfb7_done
	s_sleep 1
	s_add_u32 s3, s3, 1
	s_cmp_lt_u32 s3, 0x200000
	s_cbranch_scc1 .Lfb7_spin
.Lfb7_done:
	s_waitcnt vmcnt(0)
.LBB0_1155:
	s_or_b64 exec, exec, s[6:7]
	s_mov_b32 s3, 0x58000
	v_cmp_gt_i32_e32 vcc, s3, v186
	s_waitcnt lgkmcnt(0)
	s_barrier
	s_and_saveexec_b64 s[6:7], vcc
	s_cbranch_execz .LBB0_1164
	v_readlane_b32 s12, v244, 0
	v_readlane_b32 s14, v244, 2
	v_readlane_b32 s15, v244, 3
	s_add_u32 s8, s14, 0xe424000
	s_addc_u32 s9, s15, 0
	s_add_u32 s10, s14, 0xe9a4000
	s_addc_u32 s11, s15, 0
	v_readlane_b32 s36, v244, 35
	v_readlane_b32 s13, v244, 1
	s_add_u32 s12, s14, 0xef24000
	v_readlane_b32 s50, v244, 49
	v_readlane_b32 s51, v244, 50
	s_addc_u32 s13, s15, 0
	s_mov_b64 s[18:19], s[50:51]
	s_add_u32 s14, s18, 0x2c00
	s_addc_u32 s15, s19, 0
	s_add_u32 s16, s18, 0x5800
	v_readlane_b32 s3, v244, 33
	s_addc_u32 s17, s19, 0
	s_mov_b64 s[18:19], 0
	v_lshl_or_b32 v1, s3, 11, v1
	s_lshl_b32 s3, s2, 2
	s_mov_b32 s28, 0x2e8ba2e9
	s_movk_i32 s29, 0x1600
	s_mov_b32 s30, 0x57fff
	v_readlane_b32 s37, v244, 36
	v_readlane_b32 s38, v244, 37
	v_readlane_b32 s39, v244, 38
	v_readlane_b32 s40, v244, 39
	v_readlane_b32 s41, v244, 40
	v_readlane_b32 s42, v244, 41
	v_readlane_b32 s43, v244, 42
	v_readlane_b32 s44, v244, 43
	v_readlane_b32 s45, v244, 44
	v_readlane_b32 s46, v244, 45
	v_readlane_b32 s47, v244, 46
	v_readlane_b32 s48, v244, 47
	v_readlane_b32 s49, v244, 48
	s_branch .LBB0_1159

; __device__ __forceinline__ unsigned xb_ld(unsigned* p)              { return __hip_atomic_load(p, __ATOMIC_RELAXED, __HIP_MEMORY_SCOPE_AGENT); }
; __device__ __forceinline__ unsigned xb_add(unsigned* p, unsigned v) { return __hip_atomic_fetch_add(p, v, __ATOMIC_RELAXED, __HIP_MEMORY_SCOPE_AGENT); }
; #define XB_SPIN(cond, bar) do { unsigned _sp = 0; while (cond) { __builtin_amdgcn_s_sleep(1); \
;     if ((++_sp & 255u) == 0u) { if (xb_ld(&(bar)[XB_TMO])) break; if (_sp > XB_SPIN_CAP) { atomicAdd(&(bar)[XB_TMO], 1u); break; } } } } while (0)
; template <int WHICH>
; __device__ __forceinline__ void ln_phase(const Params& p) {
;   const int lane = threadIdx.x & 63, wid = threadIdx.x >> 6;
;   const int gw = blockIdx.x * NWAVE + wid, NGW = gridDim.x * NWAVE;
;   const float* gam = p.in[WHICH == 1 ? 20 : 26]; const float* bet = p.in[WHICH == 1 ? 21 : 27];
;   f32x4 gv[4], bv[4];
; #pragma unroll
;   for (int j = 0; j < 4; ++j) { gv[j] = *(const f32x4*)(gam + j * 256 + lane * 4); bv[j] = *(const f32x4*)(bet + j * 256 + lane * 4); }
;   for (int rp = gw; rp < MP / 2; rp += NGW) ln_rows<WHICH, 2>(p, rp * 2, lane, gv, bv);
; __device__ __forceinline__ void xcd_barrier(const XcdBarrier& b) {
;     ...
;             else XB_SPIN(xb_ld(&bar[XB_TOPGEN]) == tg, bar);
;             __builtin_amdgcn_fence(__ATOMIC_ACQUIRE, "agent");
;             xb_add(&bar[XB_XGEN(b.x)], 1u);
;             asm volatile("s_waitcnt vmcnt(0)" ::: "memory");
;         } else {
;             XB_SPIN(xb_ld(&bar[XB_XGEN(b.x)]) == gen, bar);
;             __builtin_amdgcn_fence(__ATOMIC_ACQUIRE, "agent");
;             asm volatile("s_waitcnt vmcnt(0)" ::: "memory");
;         }
;     }
;     __syncthreads();
.Lfb9_spin:
	global_load_dword v3, v2, s[6:7] sc1
	s_waitcnt vmcnt(0)
	v_cmp_ge_u32_e32 vcc, v3, v1
	s_cbranch_vccnz .Lfb9_done
	s_sleep 1
	s_add_u32 s8, s8, 1
	s_cmp_lt_u32 s8, 0x200000
	s_cbranch_scc1 .Lfb9_spin
.Lfb9_done:
	s_waitcnt vmcnt(0)
.LBB0_1310:
	s_or_b64 exec, exec, s[2:3]
	v_readlane_b32 s8, v244, 4
	v_readlane_b32 s9, v244, 5
	v_readlane_b32 s10, v244, 6
	v_readlane_b32 s11, v244, 7
	v_readlane_b32 s12, v244, 8
	v_readlane_b32 s13, v244, 9
	v_readlane_b32 s14, v244, 10
	v_readlane_b32 s15, v244, 11
	s_mov_b64 s[8:9], s[12:13]
	s_waitcnt lgkmcnt(0)
	s_barrier
	s_mov_b64 s[10:11], s[14:15]
	global_load_dwordx4 v[0:3], v188, s[8:9]
	global_load_dwordx4 v[4:7], v188, s[10:11]
	global_load_dwordx4 v[8:11], v188, s[8:9] offset:1024
	global_load_dwordx4 v[12:15], v188, s[10:11] offset:1024
	global_load_dwordx4 v[16:19], v188, s[8:9] offset:2048
	global_load_dwordx4 v[20:23], v188, s[10:11] offset:2048
	global_load_dwordx4 v[24:27], v188, s[8:9] offset:3072
	global_load_dwordx4 v[28:31], v188, s[10:11] offset:3072
	s_and_saveexec_b64 s[2:3], s[4:5]
	s_cbranch_execz .LBB0_1313
	v_mbcnt_hi_u32_b32 v32, -1, v185
	v_and_b32_e32 v33, 64, v32
	v_add_u32_e32 v33, 64, v33
	v_xor_b32_e32 v34, 1, v32
	v_cmp_lt_i32_e32 vcc, v34, v33
	v_mov_b32_e32 v191, 0
	v_readlane_b32 s4, v244, 0
	v_cndmask_b32_e32 v34, v32, v34, vcc
	v_lshlrev_b32_e32 v37, 2, v34
	v_xor_b32_e32 v34, 2, v32
	v_cmp_lt_i32_e32 vcc, v34, v33
	v_mov_b32_e32 v189, v191
	v_readlane_b32 s5, v244, 1
	v_cndmask_b32_e32 v34, v32, v34, vcc
	v_lshlrev_b32_e32 v72, 2, v34
	v_xor_b32_e32 v34, 4, v32
	v_cmp_lt_i32_e32 vcc, v34, v33
	v_readlane_b32 s6, v244, 2
	v_readlane_b32 s7, v244, 3
	v_cndmask_b32_e32 v34, v32, v34, vcc
	v_lshlrev_b32_e32 v73, 2, v34
	v_xor_b32_e32 v34, 8, v32
	v_cmp_lt_i32_e32 vcc, v34, v33
	s_lshl_b32 s7, s33, 4
	s_mov_b32 s6, 0x3a800000
	v_cndmask_b32_e32 v34, v32, v34, vcc
	v_lshlrev_b32_e32 v74, 2, v34
	v_xor_b32_e32 v34, 16, v32
	v_cmp_lt_i32_e32 vcc, v34, v33
	v_mov_b32_e32 v36, 0x3727c5ac
	s_mov_b32 s8, 0x800000
	v_cndmask_b32_e32 v34, v32, v34, vcc
	v_lshlrev_b32_e32 v75, 2, v34
	v_xor_b32_e32 v34, 32, v32
	v_cmp_lt_i32_e32 vcc, v34, v33
	s_movk_i32 s9, 0x1fff
	v_mov_b32_e32 v77, v182
	v_cndmask_b32_e32 v32, v32, v34, vcc
	v_lshlrev_b32_e32 v76, 2, v32
	v_lshl_add_u64 v[32:33], s[22:23], 0, v[190:191]
	v_lshl_add_u64 v[34:35], s[4:5], 0, v[188:189]
	s_mov_b64 s[4:5], 0
